# diff attention: softmax denominator kept per lane, reduced across quads once per pass instead of every key tile
# speedup vs baseline: 1.0283x; 1.0012x over previous
.LBB0_1310:
	s_mov_b32 s10, s2
	s_add_i32 s10, s45, s10
	s_add_i32 s2, s2, 1
	s_add_i32 s10, s10, 33
	s_cmp_lt_u32 s2, s36
	s_cselect_b32 s11, s2, s10
	s_lshl_b32 s10, s11, 6
	s_cmp_lt_i32 s11, 32
	s_cselect_b32 s11, s8, s9
	s_add_i32 s11, s11, s10
	v_add_u32_e32 v2, s11, v150
	v_mad_i64_i32 v[2:3], s[20:21], v2, s6, v[130:131]
	s_barrier
	s_waitcnt vmcnt(5)
	ds_write_b128 v154, v[84:87]
	s_waitcnt vmcnt(4)
	ds_write_b128 v155, v[88:91]
	s_waitcnt vmcnt(3)
	ds_write_b128 v154, v[92:95] offset:9216
	s_waitcnt vmcnt(2)
	ds_write_b128 v155, v[96:99] offset:9216
	s_waitcnt vmcnt(1)
	ds_write_b128 v156, v[100:103] offset:9216
	s_waitcnt vmcnt(0)
	ds_write_b128 v157, v[104:107] offset:9216
	s_waitcnt lgkmcnt(0)
	s_barrier
	global_load_dwordx4 v[84:87], v[2:3], off
	v_add_u32_e32 v2, s11, v151
	s_ashr_i32 s11, s10, 31
	v_mad_i64_i32 v[2:3], s[20:21], v2, s6, v[130:131]
	s_lshl_b64 s[10:11], s[10:11], 1
	global_load_dwordx4 v[88:91], v[2:3], off
	v_lshl_add_u64 v[2:3], v[132:133], 0, s[10:11]
	global_load_dwordx4 v[92:95], v[2:3], off
	v_lshl_add_u64 v[2:3], v[134:135], 0, s[10:11]
	global_load_dwordx4 v[96:99], v[2:3], off
	v_lshl_add_u64 v[2:3], v[136:137], 0, s[10:11]
	global_load_dwordx4 v[100:103], v[2:3], off
	v_lshl_add_u64 v[2:3], v[138:139], 0, s[10:11]
	global_load_dwordx4 v[104:107], v[2:3], off
	v_add_u32_e32 v2, v152, v153
	ds_read_b128 v[108:111], v2
	ds_read_b128 v[116:119], v2 offset:64
	s_waitcnt lgkmcnt(1)
	v_mfma_f32_16x16x32_bf16 v[112:115], v[108:111], v[72:75], 0
	ds_read_b128 v[120:123], v2 offset:2368
	ds_read_b128 v[166:169], v2 offset:4672
	v_mov_b32_e32 v174, v159
	s_waitcnt lgkmcnt(2)
	v_mfma_f32_16x16x32_bf16 v[124:127], v[116:119], v[68:71], v[112:115]
	ds_read_b128 v[170:173], v2 offset:6976
	s_nop 1
	ds_read_b128 v[112:115], v2 offset:2304
	v_mfma_f32_16x16x32_bf16 v[108:111], v[108:111], v[76:79], 0
	s_nop 2
	v_max3_f32 v3, v124, s76, v125
	v_max3_f32 v3, v3, v126, v127
	v_mfma_f32_16x16x32_bf16 v[108:111], v[116:119], v[80:83], v[108:111]
	s_waitcnt lgkmcnt(0)
	v_mfma_f32_16x16x32_bf16 v[116:119], v[112:115], v[72:75], 0
	v_mfma_f32_16x16x32_bf16 v[162:165], v[120:123], v[68:71], v[116:119]
	v_mfma_f32_16x16x32_bf16 v[112:115], v[112:115], v[76:79], 0
	s_nop 5
	ds_read_b128 v[116:119], v2 offset:4608
	v_max3_f32 v3, v3, v162, v163
	v_max3_f32 v3, v3, v164, v165
	v_mfma_f32_16x16x32_bf16 v[112:115], v[120:123], v[80:83], v[112:115]
	s_waitcnt lgkmcnt(0)
	v_mfma_f32_16x16x32_bf16 v[120:123], v[116:119], v[72:75], 0
	v_mfma_f32_16x16x32_bf16 v[176:179], v[166:169], v[68:71], v[120:123]
	s_nop 6
	ds_read_b128 v[120:123], v2 offset:6912
	v_mfma_f32_16x16x32_bf16 v[116:119], v[116:119], v[76:79], 0
	v_max3_f32 v3, v3, v176, v177
	v_max3_f32 v3, v3, v178, v179
	v_mfma_f32_16x16x32_bf16 v[116:119], v[166:169], v[80:83], v[116:119]
	s_waitcnt lgkmcnt(0)
	v_mfma_f32_16x16x32_bf16 v[166:169], v[120:123], v[72:75], 0
	v_mfma_f32_16x16x32_bf16 v[180:183], v[170:173], v[68:71], v[166:169]
	v_mfma_f32_16x16x32_bf16 v[120:123], v[120:123], v[76:79], 0
	v_mfma_f32_16x16x32_bf16 v[120:123], v[170:173], v[80:83], v[120:123]
	s_nop 5
	v_max3_f32 v3, v3, v180, v181
	v_max3_f32 v3, v3, v182, v183
	v_mov_b32_e32 v159, v3
	s_nop 1
	v_permlane16_swap_b32 v159, v3
	s_waitcnt lgkmcnt(0)
	v_max_f32_e32 v159, v159, v159
	v_max_f32_e32 v3, v3, v159
	v_mov_b32_e32 v159, v3
	s_nop 1
	v_permlane32_swap_b32 v159, v3
	s_waitcnt lgkmcnt(0)
	v_max3_f32 v159, v174, v3, v159
	v_sub_f32_e32 v3, v159, v174
	v_cmp_lt_f32_e32 vcc, 0x40b17218, v3
	s_nop 1
	v_cndmask_b32_e32 v159, v174, v159, vcc
	v_sub_f32_e32 v3, v174, v159
	v_mul_f32_e32 v3, 0x3fb8aa3b, v3
	v_exp_f32_e32 v169, v3
	v_mul_f32_e32 v3, 0xbfb8aa3b, v159
	v_fmamk_f32 v124, v124, 0x3fb8aa3b, v3
	v_exp_f32_e32 v167, v124
	v_fmamk_f32 v125, v125, 0x3fb8aa3b, v3
	v_exp_f32_e32 v168, v125
	v_fmamk_f32 v125, v126, 0x3fb8aa3b, v3
	v_exp_f32_e32 v170, v125
	v_fmamk_f32 v125, v127, 0x3fb8aa3b, v3
	v_exp_f32_e32 v171, v125
	v_fmamk_f32 v125, v162, 0x3fb8aa3b, v3
	v_add_f32_e32 v124, 0, v167
	v_exp_f32_e32 v172, v125
	v_fmamk_f32 v125, v163, 0x3fb8aa3b, v3
	v_add_f32_e32 v124, v168, v124
	v_exp_f32_e32 v173, v125
	v_fmamk_f32 v125, v164, 0x3fb8aa3b, v3
	v_add_f32_e32 v124, v170, v124
	v_exp_f32_e32 v174, v125
	v_fmamk_f32 v125, v165, 0x3fb8aa3b, v3
	v_add_f32_e32 v124, v171, v124
	v_exp_f32_e32 v175, v125
	v_fmamk_f32 v125, v176, 0x3fb8aa3b, v3
	v_add_f32_e32 v124, v172, v124
	v_exp_f32_e32 v125, v125
	v_fmamk_f32 v126, v177, 0x3fb8aa3b, v3
	v_add_f32_e32 v124, v173, v124
	v_exp_f32_e32 v126, v126
	v_fmamk_f32 v127, v178, 0x3fb8aa3b, v3
	v_add_f32_e32 v124, v174, v124
	v_exp_f32_e32 v127, v127
	v_fmamk_f32 v162, v179, 0x3fb8aa3b, v3
	v_add_f32_e32 v124, v175, v124
	v_exp_f32_e32 v162, v162
	v_fmamk_f32 v163, v180, 0x3fb8aa3b, v3
	v_add_f32_e32 v124, v125, v124
	v_exp_f32_e32 v163, v163
	v_fmamk_f32 v164, v181, 0x3fb8aa3b, v3
	v_add_f32_e32 v124, v126, v124
	v_exp_f32_e32 v164, v164
	v_fmamk_f32 v165, v182, 0x3fb8aa3b, v3
	v_add_f32_e32 v124, v127, v124
	v_exp_f32_e32 v165, v165
	v_fmac_f32_e32 v3, 0x3fb8aa3b, v183
	v_add_f32_e32 v124, v162, v124
	v_exp_f32_e32 v166, v3
	v_add_f32_e32 v124, v163, v124
	v_add_f32_e32 v124, v164, v124
	v_add_f32_e32 v124, v165, v124
	v_add_f32_e32 v3, v166, v124
	v_cmp_neq_f32_e32 vcc, 1.0, v169
	s_waitcnt lgkmcnt(0)
	s_cbranch_vccz .LBB0_1312
	ds_bpermute_b32 v178, v146, v169
	ds_bpermute_b32 v180, v144, v169
	ds_bpermute_b32 v181, v145, v169
	ds_bpermute_b32 v179, v147, v169
	s_waitcnt lgkmcnt(1)
	v_pk_mul_f32 v[66:67], v[66:67], v[180:181]
	s_waitcnt lgkmcnt(0)
	v_pk_mul_f32 v[64:65], v[64:65], v[178:179]
	v_pk_mul_f32 v[58:59], v[58:59], v[180:181]
	v_pk_mul_f32 v[56:57], v[56:57], v[178:179]
	v_pk_mul_f32 v[50:51], v[50:51], v[180:181]
	v_pk_mul_f32 v[48:49], v[48:49], v[178:179]
	v_pk_mul_f32 v[42:43], v[42:43], v[180:181]
	v_pk_mul_f32 v[40:41], v[40:41], v[178:179]
	v_pk_mul_f32 v[34:35], v[34:35], v[180:181]
	v_pk_mul_f32 v[32:33], v[32:33], v[178:179]
	v_pk_mul_f32 v[26:27], v[26:27], v[180:181]
	v_pk_mul_f32 v[24:25], v[24:25], v[178:179]
	v_pk_mul_f32 v[18:19], v[18:19], v[180:181]
	v_pk_mul_f32 v[16:17], v[16:17], v[178:179]
	v_pk_mul_f32 v[14:15], v[14:15], v[180:181]
	v_pk_mul_f32 v[12:13], v[12:13], v[178:179]
.LBB0_1312:
	v_max3_f32 v124, v108, s76, v109
	v_max3_f32 v124, v124, v110, v111
	v_max3_f32 v124, v124, v112, v113
	v_max3_f32 v124, v124, v114, v115
	v_max3_f32 v124, v124, v116, v117
	v_max3_f32 v124, v124, v118, v119
	v_max3_f32 v124, v124, v120, v121
	v_max3_f32 v124, v124, v122, v123
	v_mov_b32_e32 v177, v124
	s_nop 1
	v_permlane16_swap_b32 v177, v124
	s_waitcnt lgkmcnt(0)
	v_max_f32_e32 v177, v177, v177
	v_max_f32_e32 v124, v124, v177
	v_mov_b32_e32 v177, v124
	s_nop 1
	v_permlane32_swap_b32 v177, v124
	s_waitcnt lgkmcnt(0)
	v_max3_f32 v124, v161, v124, v177
	v_sub_f32_e32 v177, v124, v161
	v_cmp_lt_f32_e32 vcc, 0x40b17218, v177
	s_nop 1
	v_cndmask_b32_e32 v124, v161, v124, vcc
	v_mul_f32_e32 v178, 0xbfb8aa3b, v124
	v_fmamk_f32 v108, v108, 0x3fb8aa3b, v178
	v_fmamk_f32 v109, v109, 0x3fb8aa3b, v178
	v_exp_f32_e32 v108, v108
	v_fmamk_f32 v110, v110, 0x3fb8aa3b, v178
	v_exp_f32_e32 v109, v109
	v_fmamk_f32 v111, v111, 0x3fb8aa3b, v178
	v_exp_f32_e32 v110, v110
	v_fmamk_f32 v112, v112, 0x3fb8aa3b, v178
	v_exp_f32_e32 v111, v111
	v_fmamk_f32 v113, v113, 0x3fb8aa3b, v178
	v_exp_f32_e32 v112, v112
	v_add_f32_e32 v177, 0, v108
	v_fmamk_f32 v114, v114, 0x3fb8aa3b, v178
	v_exp_f32_e32 v113, v113
	v_add_f32_e32 v177, v109, v177
	v_add_f32_e32 v177, v110, v177
	v_exp_f32_e32 v114, v114
	v_fmamk_f32 v115, v115, 0x3fb8aa3b, v178
	v_add_f32_e32 v179, v111, v177
	v_exp_f32_e32 v177, v115
	v_fmamk_f32 v116, v116, 0x3fb8aa3b, v178
	v_add_f32_e32 v115, v112, v179
	v_exp_f32_e32 v116, v116
	v_fmamk_f32 v117, v117, 0x3fb8aa3b, v178
	v_add_f32_e32 v115, v113, v115
	v_exp_f32_e32 v117, v117
	v_fmamk_f32 v118, v118, 0x3fb8aa3b, v178
	v_add_f32_e32 v115, v114, v115
	v_exp_f32_e32 v118, v118
	v_fmamk_f32 v119, v119, 0x3fb8aa3b, v178
	v_add_f32_e32 v115, v177, v115
	v_exp_f32_e32 v119, v119
	v_fmamk_f32 v120, v120, 0x3fb8aa3b, v178
	v_add_f32_e32 v115, v116, v115
	v_exp_f32_e32 v120, v120
	v_fmamk_f32 v121, v121, 0x3fb8aa3b, v178
	v_add_f32_e32 v115, v117, v115
	v_exp_f32_e32 v121, v121
	v_fmamk_f32 v122, v122, 0x3fb8aa3b, v178
	v_add_f32_e32 v115, v118, v115
	v_exp_f32_e32 v122, v122
	v_fmac_f32_e32 v178, 0x3fb8aa3b, v123
	v_add_f32_e32 v115, v119, v115
	v_exp_f32_e32 v123, v178
	v_add_f32_e32 v115, v120, v115
	v_add_f32_e32 v115, v121, v115
	v_add_f32_e32 v115, v122, v115
	v_add_f32_e32 v115, v123, v115
	v_sub_f32_e32 v161, v161, v124
	v_mul_f32_e32 v161, 0x3fb8aa3b, v161
	v_exp_f32_e32 v161, v161
	s_waitcnt lgkmcnt(0)
	v_cmp_neq_f32_e32 vcc, 1.0, v161
	s_cbranch_vccz .LBB0_1314
	ds_bpermute_b32 v180, v146, v161
	ds_bpermute_b32 v182, v144, v161
	ds_bpermute_b32 v183, v145, v161
	ds_bpermute_b32 v181, v147, v161
	s_waitcnt lgkmcnt(1)
	v_pk_mul_f32 v[62:63], v[62:63], v[182:183]
	s_waitcnt lgkmcnt(0)
	v_pk_mul_f32 v[60:61], v[60:61], v[180:181]
	v_pk_mul_f32 v[54:55], v[54:55], v[182:183]
	v_pk_mul_f32 v[52:53], v[52:53], v[180:181]
	v_pk_mul_f32 v[46:47], v[46:47], v[182:183]
	v_pk_mul_f32 v[44:45], v[44:45], v[180:181]
	v_pk_mul_f32 v[38:39], v[38:39], v[182:183]
	v_pk_mul_f32 v[36:37], v[36:37], v[180:181]
	v_pk_mul_f32 v[30:31], v[30:31], v[182:183]
	v_pk_mul_f32 v[28:29], v[28:29], v[180:181]
	v_pk_mul_f32 v[22:23], v[22:23], v[182:183]
	v_pk_mul_f32 v[20:21], v[20:21], v[180:181]
	v_pk_mul_f32 v[10:11], v[10:11], v[182:183]
	v_pk_mul_f32 v[8:9], v[8:9], v[180:181]
	v_pk_mul_f32 v[6:7], v[6:7], v[182:183]
	v_pk_mul_f32 v[4:5], v[4:5], v[180:181]
.LBB0_1314:
	v_fmac_f32_e32 v3, v0, v169
	v_add_u32_e32 v0, 0x2000, v158
	v_cvt_pk_bf16_f32 v168, v167, v168
	v_cvt_pk_bf16_f32 v169, v170, v171
	v_cvt_pk_bf16_f32 v170, v172, v173
	v_cvt_pk_bf16_f32 v171, v174, v175
	v_cvt_pk_bf16_f32 v172, v108, v109
	v_cvt_pk_bf16_f32 v173, v110, v111
	v_cvt_pk_bf16_f32 v174, v112, v113
	v_cvt_pk_bf16_f32 v175, v114, v177
	ds_read2_b64 v[108:111], v0 offset0:128 offset1:132
	s_waitcnt lgkmcnt(1)
	s_waitcnt lgkmcnt(0)
	v_mfma_f32_16x16x32_bf16 v[64:67], v[168:171], v[108:111], v[64:67]
	v_fmac_f32_e32 v115, v160, v161
	v_cvt_pk_bf16_f32 v160, v125, v126
	v_cvt_pk_bf16_f32 v161, v127, v162
	v_mfma_f32_16x16x32_bf16 v[60:63], v[172:175], v[108:111], v[60:63]
	v_add_u32_e32 v109, 0x2800, v158
	ds_read2_b64 v[110:113], v109 offset0:160 offset1:164
	v_cvt_pk_bf16_f32 v162, v163, v164
	v_cvt_pk_bf16_f32 v163, v165, v166
	v_cvt_pk_bf16_f32 v116, v116, v117
	v_cvt_pk_bf16_f32 v117, v118, v119
	v_cvt_pk_bf16_f32 v118, v120, v121
	v_cvt_pk_bf16_f32 v119, v122, v123
	ds_read2_b64 v[120:123], v0 offset0:136 offset1:140
	v_add_u32_e32 v108, 0x3000, v158
	s_waitcnt lgkmcnt(1)
	v_mfma_f32_16x16x32_bf16 v[56:59], v[168:171], v[110:113], v[56:59]
	v_add_u32_e32 v114, 0x6000, v158
	s_add_i32 s10, s45, s2
	s_cmp_eq_u32 s10, 3
	v_mfma_f32_16x16x32_bf16 v[52:55], v[172:175], v[110:113], v[52:55]
	ds_read2_b64 v[110:113], v108 offset0:192 offset1:196
	s_waitcnt lgkmcnt(1)
	v_mfma_f32_16x16x32_bf16 v[64:67], v[160:163], v[120:123], v[64:67]
	v_mfma_f32_16x16x32_bf16 v[60:63], v[116:119], v[120:123], v[60:63]
	ds_read2_b64 v[120:123], v109 offset0:168 offset1:172
	s_waitcnt lgkmcnt(1)
	v_mfma_f32_16x16x32_bf16 v[48:51], v[168:171], v[110:113], v[48:51]
	v_mfma_f32_16x16x32_bf16 v[44:47], v[172:175], v[110:113], v[44:47]
	v_add_u32_e32 v110, 0x3800, v158
	ds_read2_b64 v[176:179], v110 offset0:224 offset1:228
	v_add_u32_e32 v111, 0x4800, v158
	s_waitcnt lgkmcnt(1)
	v_mfma_f32_16x16x32_bf16 v[56:59], v[160:163], v[120:123], v[56:59]
	v_add_u32_e32 v112, 0x5000, v158
	v_add_u32_e32 v113, 0x5800, v158
	v_mfma_f32_16x16x32_bf16 v[52:55], v[116:119], v[120:123], v[52:55]
	ds_read2_b64 v[120:123], v108 offset0:200 offset1:204
	s_waitcnt lgkmcnt(0)
	v_mfma_f32_16x16x32_bf16 v[48:51], v[160:163], v[120:123], v[48:51]
	v_mfma_f32_16x16x32_bf16 v[44:47], v[116:119], v[120:123], v[44:47]
	ds_read2_b64 v[120:123], v110 offset0:232 offset1:236
	v_mfma_f32_16x16x32_bf16 v[40:43], v[168:171], v[176:179], v[40:43]
	v_mfma_f32_16x16x32_bf16 v[36:39], v[172:175], v[176:179], v[36:39]
	ds_read2_b64 v[176:179], v111 offset1:4
	s_waitcnt lgkmcnt(1)
	v_mfma_f32_16x16x32_bf16 v[40:43], v[160:163], v[120:123], v[40:43]
	v_mfma_f32_16x16x32_bf16 v[36:39], v[116:119], v[120:123], v[36:39]
	ds_read2_b64 v[120:123], v111 offset0:8 offset1:12
	s_waitcnt lgkmcnt(1)
	v_mfma_f32_16x16x32_bf16 v[32:35], v[168:171], v[176:179], v[32:35]
	v_mfma_f32_16x16x32_bf16 v[28:31], v[172:175], v[176:179], v[28:31]
	ds_read2_b64 v[176:179], v112 offset0:32 offset1:36
	s_waitcnt lgkmcnt(1)
	v_mfma_f32_16x16x32_bf16 v[32:35], v[160:163], v[120:123], v[32:35]
	v_mfma_f32_16x16x32_bf16 v[28:31], v[116:119], v[120:123], v[28:31]
	ds_read2_b64 v[120:123], v112 offset0:40 offset1:44
	s_waitcnt lgkmcnt(1)
	v_mfma_f32_16x16x32_bf16 v[24:27], v[168:171], v[176:179], v[24:27]
	v_mfma_f32_16x16x32_bf16 v[20:23], v[172:175], v[176:179], v[20:23]
	ds_read2_b64 v[176:179], v113 offset0:64 offset1:68
	s_waitcnt lgkmcnt(1)
	v_mfma_f32_16x16x32_bf16 v[24:27], v[160:163], v[120:123], v[24:27]
	v_mfma_f32_16x16x32_bf16 v[20:23], v[116:119], v[120:123], v[20:23]
	ds_read2_b64 v[120:123], v113 offset0:72 offset1:76
	s_waitcnt lgkmcnt(1)
	v_mfma_f32_16x16x32_bf16 v[16:19], v[168:171], v[176:179], v[16:19]
	v_mfma_f32_16x16x32_bf16 v[8:11], v[172:175], v[176:179], v[8:11]
	ds_read2_b64 v[176:179], v114 offset0:96 offset1:100
	s_waitcnt lgkmcnt(1)
	v_mfma_f32_16x16x32_bf16 v[16:19], v[160:163], v[120:123], v[16:19]
	v_mfma_f32_16x16x32_bf16 v[8:11], v[116:119], v[120:123], v[8:11]
	ds_read2_b64 v[120:123], v114 offset0:104 offset1:108
	s_waitcnt lgkmcnt(1)
	v_mfma_f32_16x16x32_bf16 v[12:15], v[168:171], v[176:179], v[12:15]
	v_mfma_f32_16x16x32_bf16 v[4:7], v[172:175], v[176:179], v[4:7]
	s_waitcnt lgkmcnt(0)
	v_mfma_f32_16x16x32_bf16 v[12:15], v[160:163], v[120:123], v[12:15]
	v_mfma_f32_16x16x32_bf16 v[4:7], v[116:119], v[120:123], v[4:7]
	s_cbranch_scc1 .LBB0_1316
	v_mov_b32_e32 v161, v124
	v_mov_b32_e32 v160, v115
	v_mov_b32_e32 v0, v3
	s_branch .LBB0_1310
.LBB0_1316:
	s_barrier
	s_waitcnt vmcnt(5)
	ds_write_b128 v154, v[84:87]
	s_waitcnt vmcnt(4)
	ds_write_b128 v155, v[88:91]
	s_waitcnt vmcnt(3)
	ds_write_b128 v154, v[92:95] offset:9216
	s_waitcnt vmcnt(2)
	ds_write_b128 v155, v[96:99] offset:9216
	s_waitcnt vmcnt(1)
	ds_write_b128 v156, v[100:103] offset:9216
	s_waitcnt vmcnt(0)
	ds_write_b128 v157, v[104:107] offset:9216
	s_waitcnt lgkmcnt(0)
	s_barrier
	ds_read_b128 v[84:87], v2
	ds_read_b128 v[92:95], v2 offset:64
	s_waitcnt lgkmcnt(1)
	v_mfma_f32_16x16x32_bf16 v[88:91], v[84:87], v[72:75], 0
	ds_read_b128 v[100:103], v2 offset:2368
	ds_read_b128 v[116:119], v2 offset:4672
	v_mfma_f32_16x16x32_bf16 v[84:87], v[84:87], v[76:79], 0
	s_waitcnt lgkmcnt(2)
	v_mfma_f32_16x16x32_bf16 v[96:99], v[92:95], v[68:71], v[88:91]
	v_mfma_f32_16x16x32_bf16 v[92:95], v[92:95], v[80:83], v[84:87]
	s_nop 4
	ds_read_b128 v[84:87], v2 offset:2304
	s_waitcnt lgkmcnt(0)
	v_mfma_f32_16x16x32_bf16 v[88:91], v[84:87], v[72:75], 0
	v_mfma_f32_16x16x32_bf16 v[84:87], v[84:87], v[76:79], 0
	v_mfma_f32_16x16x32_bf16 v[104:107], v[100:103], v[68:71], v[88:91]
	v_mfma_f32_16x16x32_bf16 v[88:91], v[100:103], v[80:83], v[84:87]
	s_nop 5
	ds_read_b128 v[84:87], v2 offset:4608
	s_waitcnt lgkmcnt(0)
	v_mfma_f32_16x16x32_bf16 v[100:103], v[84:87], v[72:75], 0
	v_mfma_f32_16x16x32_bf16 v[84:87], v[84:87], v[76:79], 0
	v_mfma_f32_16x16x32_bf16 v[100:103], v[116:119], v[68:71], v[100:103]
	v_mfma_f32_16x16x32_bf16 v[84:87], v[116:119], v[80:83], v[84:87]
	ds_read_b128 v[116:119], v2 offset:6912
	s_waitcnt lgkmcnt(0)
	v_mfma_f32_16x16x32_bf16 v[72:75], v[116:119], v[72:75], 0
	v_mfma_f32_16x16x32_bf16 v[76:79], v[116:119], v[76:79], 0
	ds_read_b128 v[116:119], v2 offset:6976
	v_max3_f32 v2, v96, s76, v97
	v_max3_f32 v2, v2, v98, v99
	s_waitcnt lgkmcnt(0)
	v_mfma_f32_16x16x32_bf16 v[120:123], v[116:119], v[68:71], v[72:75]
	v_max3_f32 v2, v2, v104, v105
	v_max3_f32 v2, v2, v106, v107
	v_max3_f32 v2, v2, v100, v101
	v_max3_f32 v2, v2, v102, v103
	s_nop 3
	v_max3_f32 v2, v2, v120, v121
	v_max3_f32 v2, v2, v122, v123
	v_mov_b32_e32 v72, v2
	s_nop 1
	v_permlane16_swap_b32 v72, v2
	v_mfma_f32_16x16x32_bf16 v[68:71], v[116:119], v[80:83], v[76:79]
	s_waitcnt lgkmcnt(0)
	v_max_f32_e32 v72, v72, v72
	v_max_f32_e32 v2, v2, v72
	v_mov_b32_e32 v72, v2
	s_nop 1
	v_permlane32_swap_b32 v72, v2
	s_waitcnt lgkmcnt(0)
	v_max3_f32 v2, v159, v2, v72
	v_sub_f32_e32 v72, v2, v159
	v_cmp_lt_f32_e32 vcc, 0x40b17218, v72
	s_nop 1
	v_cndmask_b32_e32 v2, v159, v2, vcc
	v_sub_f32_e32 v72, v159, v2
	v_mul_f32_e32 v78, 0xbfb8aa3b, v2
	v_mul_f32_e32 v72, 0x3fb8aa3b, v72
	v_fmamk_f32 v2, v96, 0x3fb8aa3b, v78
	v_exp_f32_e32 v80, v72
	v_exp_f32_e32 v79, v2
	v_fmamk_f32 v72, v97, 0x3fb8aa3b, v78
	v_exp_f32_e32 v81, v72
	v_fmamk_f32 v72, v98, 0x3fb8aa3b, v78
	v_exp_f32_e32 v82, v72
	v_fmamk_f32 v72, v99, 0x3fb8aa3b, v78
	v_exp_f32_e32 v83, v72
	v_fmamk_f32 v72, v104, 0x3fb8aa3b, v78
	v_add_f32_e32 v2, 0, v79
	v_exp_f32_e32 v96, v72
	v_fmamk_f32 v72, v105, 0x3fb8aa3b, v78
	v_add_f32_e32 v2, v81, v2
	v_exp_f32_e32 v97, v72
	v_fmamk_f32 v72, v106, 0x3fb8aa3b, v78
	v_add_f32_e32 v2, v82, v2
	v_exp_f32_e32 v98, v72
	v_fmamk_f32 v72, v107, 0x3fb8aa3b, v78
	v_add_f32_e32 v2, v83, v2
	v_exp_f32_e32 v99, v72
	v_add_f32_e32 v2, v96, v2
	v_add_f32_e32 v2, v97, v2
	v_add_f32_e32 v2, v98, v2
	v_add_f32_e32 v72, v99, v2
	v_fmamk_f32 v2, v100, 0x3fb8aa3b, v78
	v_exp_f32_e32 v2, v2
	v_cmp_neq_f32_e32 vcc, 1.0, v80
	v_add_f32_e32 v73, v2, v72
	v_fmamk_f32 v72, v101, 0x3fb8aa3b, v78
	v_exp_f32_e32 v72, v72
	s_nop 0
	v_add_f32_e32 v74, v72, v73
	v_fmamk_f32 v73, v102, 0x3fb8aa3b, v78
	v_exp_f32_e32 v73, v73
	s_nop 0
	v_add_f32_e32 v75, v73, v74
	v_fmamk_f32 v74, v103, 0x3fb8aa3b, v78
	v_exp_f32_e32 v74, v74
	s_nop 0
	v_add_f32_e32 v76, v74, v75
	v_fmamk_f32 v75, v120, 0x3fb8aa3b, v78
	v_exp_f32_e32 v75, v75
	s_nop 0
	v_add_f32_e32 v77, v75, v76
	v_fmamk_f32 v76, v121, 0x3fb8aa3b, v78
	v_exp_f32_e32 v76, v76
	s_nop 0
	v_add_f32_e32 v100, v76, v77
	v_fmamk_f32 v77, v122, 0x3fb8aa3b, v78
	v_exp_f32_e32 v77, v77
	v_fmac_f32_e32 v78, 0x3fb8aa3b, v123
	v_exp_f32_e32 v78, v78
	v_add_f32_e32 v100, v77, v100
	v_add_f32_e32 v100, v78, v100
	s_waitcnt lgkmcnt(0)
	s_cbranch_vccz .LBB0_1318
	ds_bpermute_b32 v102, v146, v80
	ds_bpermute_b32 v104, v144, v80
	ds_bpermute_b32 v105, v145, v80
	ds_bpermute_b32 v103, v147, v80
	s_waitcnt lgkmcnt(1)
	v_pk_mul_f32 v[66:67], v[66:67], v[104:105]
	s_waitcnt lgkmcnt(0)
	v_pk_mul_f32 v[64:65], v[64:65], v[102:103]
	v_pk_mul_f32 v[58:59], v[58:59], v[104:105]
	v_pk_mul_f32 v[56:57], v[56:57], v[102:103]
	v_pk_mul_f32 v[50:51], v[50:51], v[104:105]
	v_pk_mul_f32 v[48:49], v[48:49], v[102:103]
	v_pk_mul_f32 v[42:43], v[42:43], v[104:105]
	v_pk_mul_f32 v[40:41], v[40:41], v[102:103]
	v_pk_mul_f32 v[34:35], v[34:35], v[104:105]
	v_pk_mul_f32 v[32:33], v[32:33], v[102:103]
	v_pk_mul_f32 v[26:27], v[26:27], v[104:105]
	v_pk_mul_f32 v[24:25], v[24:25], v[102:103]
	v_pk_mul_f32 v[18:19], v[18:19], v[104:105]
	v_pk_mul_f32 v[16:17], v[16:17], v[102:103]
	v_pk_mul_f32 v[14:15], v[14:15], v[104:105]
	v_pk_mul_f32 v[12:13], v[12:13], v[102:103]
.LBB0_1318:
	v_max3_f32 v102, v92, s76, v93
	v_max3_f32 v102, v102, v94, v95
	v_max3_f32 v102, v102, v88, v89
	v_max3_f32 v102, v102, v90, v91
	v_max3_f32 v102, v102, v84, v85
	v_max3_f32 v102, v102, v86, v87
	v_max3_f32 v102, v102, v68, v69
	v_max3_f32 v102, v102, v70, v71
	v_mov_b32_e32 v103, v102
	s_nop 1
	v_permlane16_swap_b32 v103, v102
	s_waitcnt lgkmcnt(0)
	v_max_f32_e32 v103, v103, v103
	v_max_f32_e32 v102, v102, v103
	v_mov_b32_e32 v103, v102
	s_nop 1
	v_permlane32_swap_b32 v103, v102
	s_waitcnt lgkmcnt(0)
	v_max3_f32 v103, v124, v102, v103
	v_sub_f32_e32 v102, v103, v124
	v_cmp_lt_f32_e32 vcc, 0x40b17218, v102
	s_nop 1
	v_cndmask_b32_e32 v103, v124, v103, vcc
	v_mul_f32_e32 v104, 0xbfb8aa3b, v103
	v_fmamk_f32 v92, v92, 0x3fb8aa3b, v104
	v_exp_f32_e32 v92, v92
	v_fmamk_f32 v93, v93, 0x3fb8aa3b, v104
	v_exp_f32_e32 v93, v93
	v_fmamk_f32 v94, v94, 0x3fb8aa3b, v104
	v_exp_f32_e32 v94, v94
	v_fmamk_f32 v95, v95, 0x3fb8aa3b, v104
	v_exp_f32_e32 v95, v95
	v_sub_f32_e32 v102, v124, v103
	v_add_f32_e32 v103, 0, v92
	v_add_f32_e32 v103, v93, v103
	v_add_f32_e32 v103, v94, v103
	v_fmamk_f32 v88, v88, 0x3fb8aa3b, v104
	v_add_f32_e32 v105, v95, v103
	v_exp_f32_e32 v103, v88
	v_fmamk_f32 v89, v89, 0x3fb8aa3b, v104
	v_exp_f32_e32 v89, v89
	v_fmamk_f32 v90, v90, 0x3fb8aa3b, v104
	v_exp_f32_e32 v90, v90
	v_fmamk_f32 v91, v91, 0x3fb8aa3b, v104
	v_exp_f32_e32 v91, v91
	v_add_f32_e32 v88, v103, v105
	v_add_f32_e32 v88, v89, v88
	v_add_f32_e32 v88, v90, v88
	v_fmamk_f32 v84, v84, 0x3fb8aa3b, v104
	v_add_f32_e32 v105, v91, v88
	v_exp_f32_e32 v88, v84
	v_fmamk_f32 v85, v85, 0x3fb8aa3b, v104
	v_exp_f32_e32 v85, v85
	v_fmamk_f32 v86, v86, 0x3fb8aa3b, v104
	v_exp_f32_e32 v86, v86
	v_fmamk_f32 v87, v87, 0x3fb8aa3b, v104
	v_exp_f32_e32 v87, v87
	v_fmamk_f32 v68, v68, 0x3fb8aa3b, v104
	v_add_f32_e32 v84, v88, v105
	v_exp_f32_e32 v68, v68
	v_fmamk_f32 v69, v69, 0x3fb8aa3b, v104
	v_add_f32_e32 v84, v85, v84
	v_exp_f32_e32 v69, v69
	v_fmamk_f32 v70, v70, 0x3fb8aa3b, v104
	v_add_f32_e32 v84, v86, v84
	v_exp_f32_e32 v70, v70
	v_fmac_f32_e32 v104, 0x3fb8aa3b, v71
	v_add_f32_e32 v84, v87, v84
	v_exp_f32_e32 v71, v104
	v_add_f32_e32 v84, v68, v84
	v_add_f32_e32 v84, v69, v84
	v_add_f32_e32 v84, v70, v84
	v_add_f32_e32 v84, v71, v84
	v_mul_f32_e32 v102, 0x3fb8aa3b, v102
	v_exp_f32_e32 v102, v102
	s_waitcnt lgkmcnt(0)
	v_cmp_neq_f32_e32 vcc, 1.0, v102
	s_cbranch_vccz .LBB0_1320
	ds_bpermute_b32 v106, v146, v102
	ds_bpermute_b32 v116, v144, v102
	ds_bpermute_b32 v117, v145, v102
	ds_bpermute_b32 v107, v147, v102
	s_waitcnt lgkmcnt(1)
	v_pk_mul_f32 v[62:63], v[62:63], v[116:117]
	s_waitcnt lgkmcnt(0)
	v_pk_mul_f32 v[60:61], v[60:61], v[106:107]
	v_pk_mul_f32 v[54:55], v[54:55], v[116:117]
	v_pk_mul_f32 v[52:53], v[52:53], v[106:107]
	v_pk_mul_f32 v[46:47], v[46:47], v[116:117]
	v_pk_mul_f32 v[44:45], v[44:45], v[106:107]
	v_pk_mul_f32 v[38:39], v[38:39], v[116:117]
	v_pk_mul_f32 v[36:37], v[36:37], v[106:107]
	v_pk_mul_f32 v[30:31], v[30:31], v[116:117]
	v_pk_mul_f32 v[28:29], v[28:29], v[106:107]
	v_pk_mul_f32 v[22:23], v[22:23], v[116:117]
	v_pk_mul_f32 v[20:21], v[20:21], v[106:107]
	v_pk_mul_f32 v[10:11], v[10:11], v[116:117]
	v_pk_mul_f32 v[8:9], v[8:9], v[106:107]
	v_pk_mul_f32 v[6:7], v[6:7], v[116:117]
	v_pk_mul_f32 v[4:5], v[4:5], v[106:107]
.LBB0_1320:
	s_waitcnt lgkmcnt(0)
	v_fmac_f32_e32 v84, v115, v102
	v_mov_b32_e32 v115, v100
	v_fmac_f32_e32 v115, v3, v80
	v_cvt_pk_bf16_f32 v80, v79, v81
	v_cvt_pk_bf16_f32 v81, v82, v83
	v_cvt_pk_bf16_f32 v82, v96, v97
	v_cvt_pk_bf16_f32 v83, v98, v99
	v_cvt_pk_bf16_f32 v92, v92, v93
	v_cvt_pk_bf16_f32 v93, v94, v95
	v_cvt_pk_bf16_f32 v94, v103, v89
	v_cvt_pk_bf16_f32 v95, v90, v91
	ds_read2_b64 v[96:99], v0 offset0:128 offset1:132
	s_waitcnt lgkmcnt(0)
	v_mfma_f32_16x16x32_bf16 v[64:67], v[80:83], v[96:99], v[64:67]
	v_cvt_pk_bf16_f32 v72, v2, v72
	v_cvt_pk_bf16_f32 v73, v73, v74
	v_cvt_pk_bf16_f32 v74, v75, v76
	v_mfma_f32_16x16x32_bf16 v[60:63], v[92:95], v[96:99], v[60:63]
	ds_read2_b64 v[96:99], v109 offset0:160 offset1:164
	v_cvt_pk_bf16_f32 v75, v77, v78
	v_cvt_pk_bf16_f32 v76, v88, v85
	s_waitcnt lgkmcnt(0)
	v_mfma_f32_16x16x32_bf16 v[56:59], v[80:83], v[96:99], v[56:59]
	v_cvt_pk_bf16_f32 v77, v86, v87
	v_cvt_pk_bf16_f32 v78, v68, v69
	v_cvt_pk_bf16_f32 v79, v70, v71
	v_mfma_f32_16x16x32_bf16 v[52:55], v[92:95], v[96:99], v[52:55]
	ds_read2_b64 v[96:99], v108 offset0:192 offset1:196
	s_mov_b64 s[42:43], -1
	s_waitcnt lgkmcnt(0)
	v_mfma_f32_16x16x32_bf16 v[48:51], v[80:83], v[96:99], v[48:51]
	v_mfma_f32_16x16x32_bf16 v[44:47], v[92:95], v[96:99], v[44:47]
	ds_read2_b64 v[96:99], v110 offset0:224 offset1:228
	s_waitcnt lgkmcnt(0)
	v_mfma_f32_16x16x32_bf16 v[100:103], v[80:83], v[96:99], v[40:43]
	v_mfma_f32_16x16x32_bf16 v[96:99], v[92:95], v[96:99], v[36:39]
	s_nop 2
	ds_read2_b64 v[36:39], v111 offset1:4
	s_waitcnt lgkmcnt(0)
	v_mfma_f32_16x16x32_bf16 v[104:107], v[80:83], v[36:39], v[32:35]
	s_nop 2
	ds_read2_b64 v[32:35], v112 offset0:32 offset1:36
	s_waitcnt lgkmcnt(0)
	v_mfma_f32_16x16x32_bf16 v[116:119], v[92:95], v[32:35], v[20:23]
	s_nop 2
	ds_read2_b64 v[20:23], v113 offset0:64 offset1:68
	s_waitcnt lgkmcnt(0)
	v_mfma_f32_16x16x32_bf16 v[124:127], v[92:95], v[20:23], v[8:11]
	s_nop 2
	ds_read2_b64 v[8:11], v114 offset0:96 offset1:100
	v_mfma_f32_16x16x32_bf16 v[28:31], v[92:95], v[36:39], v[28:31]
	v_mfma_f32_16x16x32_bf16 v[24:27], v[80:83], v[32:35], v[24:27]
	v_mfma_f32_16x16x32_bf16 v[120:123], v[80:83], v[20:23], v[16:19]
	s_waitcnt lgkmcnt(0)
	v_mfma_f32_16x16x32_bf16 v[80:83], v[80:83], v[8:11], v[12:15]
	s_nop 0
	ds_read2_b64 v[18:21], v111 offset0:8 offset1:12
	v_mfma_f32_16x16x32_bf16 v[90:93], v[92:95], v[8:11], v[4:7]
	ds_read2_b64 v[10:13], v108 offset0:200 offset1:204
	ds_read2_b64 v[14:17], v110 offset0:232 offset1:236
	s_nop 0
	ds_read2_b64 v[6:9], v109 offset0:168 offset1:172
	ds_read2_b64 v[2:5], v0 offset0:136 offset1:140
	v_mov_b32_e32 v184, v115
	s_nop 1
	v_permlane16_swap_b32 v184, v115
	v_add_f32_e32 v115, v115, v184
	v_mov_b32_e32 v184, v115
	s_nop 1
	v_permlane32_swap_b32 v184, v115
	v_add_f32_e32 v115, v115, v184
	v_div_scale_f32 v0, s[10:11], v115, v115, 1.0
	s_waitcnt lgkmcnt(1)
	v_mfma_f32_16x16x32_bf16 v[38:41], v[72:75], v[6:9], v[56:59]
	v_mfma_f32_16x16x32_bf16 v[6:9], v[76:79], v[6:9], v[52:55]
	s_nop 2
	v_rcp_f32_e32 v54, v0
	v_mfma_f32_16x16x32_bf16 v[50:53], v[72:75], v[10:13], v[48:51]
	v_fma_f32 v55, -v0, v54, 1.0
	v_fmac_f32_e32 v54, v55, v54
	v_div_scale_f32 v55, vcc, 1.0, v115, 1.0
	v_mul_f32_e32 v56, v55, v54
	v_fma_f32 v57, -v0, v56, v55
	v_mfma_f32_16x16x32_bf16 v[10:13], v[76:79], v[10:13], v[44:47]
	v_fmac_f32_e32 v56, v57, v54
	v_fma_f32 v0, -v0, v56, v55
	v_div_fmas_f32 v0, v0, v54, v56
	v_mfma_f32_16x16x32_bf16 v[46:49], v[72:75], v[18:21], v[104:107]
	v_div_fixup_f32 v0, v0, v115, 1.0
	ds_bpermute_b32 v54, v146, v0
	ds_bpermute_b32 v55, v147, v0
	v_mfma_f32_16x16x32_bf16 v[18:21], v[76:79], v[18:21], v[28:31]
	s_nop 2
	ds_read2_b64 v[28:31], v112 offset0:40 offset1:44
	s_waitcnt lgkmcnt(3)
	v_mfma_f32_16x16x32_bf16 v[34:37], v[72:75], v[2:5], v[64:67]
	s_waitcnt lgkmcnt(1)
	v_pk_mul_f32 v[56:57], v[46:47], v[54:55]
	s_waitcnt lgkmcnt(0)
	v_mfma_f32_16x16x32_bf16 v[86:89], v[72:75], v[28:31], v[24:27]
	v_mul_f32_e64 v64, v50, v54
	v_mul_f32_e64 v65, v51, v55
	v_mfma_f32_16x16x32_bf16 v[22:25], v[76:79], v[28:31], v[116:119]
	ds_read2_b64 v[26:29], v113 offset0:72 offset1:76
	ds_read2_b64 v[30:33], v114 offset0:104 offset1:108
	s_nop 2
	v_pk_mul_f32 v[58:59], v[86:87], v[54:55]
	v_mfma_f32_16x16x32_bf16 v[2:5], v[76:79], v[2:5], v[60:63]
	s_nop 2
	v_mul_f32_e64 v60, v34, v54
	v_mul_f32_e64 v61, v35, v55
	ds_bpermute_b32 v34, v144, v0
	ds_bpermute_b32 v35, v145, v0
	v_mfma_f32_16x16x32_bf16 v[42:45], v[72:75], v[14:17], v[100:103]
	v_mov_b32_e32 v184, v84
	s_nop 1
	v_permlane16_swap_b32 v184, v84
	v_add_f32_e32 v84, v84, v184
	v_mov_b32_e32 v184, v84
	s_nop 1
	v_permlane32_swap_b32 v184, v84
	v_add_f32_e32 v84, v84, v184
	v_div_scale_f32 v0, s[10:11], v84, v84, 1.0
	v_pk_mul_f32 v[62:63], v[38:39], v[54:55]
	v_mfma_f32_16x16x32_bf16 v[14:17], v[76:79], v[14:17], v[96:99]
	s_waitcnt lgkmcnt(0)
	v_pk_mul_f32 v[68:69], v[36:37], v[34:35]
	s_nop 2
	v_pk_mul_f32 v[66:67], v[42:43], v[54:55]
	v_pk_mul_f32 v[70:71], v[40:41], v[34:35]
	v_mfma_f32_16x16x32_bf16 v[94:97], v[72:75], v[26:29], v[120:123]
	v_mfma_f32_16x16x32_bf16 v[80:83], v[72:75], v[30:33], v[80:83]
	v_mul_f32_e64 v72, v52, v34
	v_mul_f32_e64 v73, v53, v35
	s_nop 4
	v_pk_mul_f32 v[46:47], v[94:95], v[54:55]
	v_pk_mul_f32 v[74:75], v[44:45], v[34:35]
	v_pk_mul_f32 v[52:53], v[48:49], v[34:35]
	v_pk_mul_f32 v[44:45], v[96:97], v[34:35]
	v_pk_mul_f32 v[50:51], v[80:81], v[54:55]
	v_pk_mul_f32 v[54:55], v[88:89], v[34:35]
	v_pk_mul_f32 v[48:49], v[82:83], v[34:35]
	v_rcp_f32_e32 v34, v0
	v_mfma_f32_16x16x32_bf16 v[26:29], v[76:79], v[26:29], v[124:127]
	v_fma_f32 v35, -v0, v34, 1.0
	v_fmac_f32_e32 v34, v35, v34
	v_div_scale_f32 v35, vcc, 1.0, v84, 1.0
	v_mul_f32_e32 v36, v35, v34
	v_fma_f32 v37, -v0, v36, v35
	v_fmac_f32_e32 v36, v37, v34
	v_fma_f32 v0, -v0, v36, v35
	v_div_fmas_f32 v0, v0, v34, v36
	v_div_fixup_f32 v0, v0, v84, 1.0
	ds_bpermute_b32 v42, v146, v0
	ds_bpermute_b32 v43, v147, v0
	v_mfma_f32_16x16x32_bf16 v[30:33], v[76:79], v[30:33], v[90:93]
	s_andn2_b64 vcc, exec, s[40:41]
	s_waitcnt lgkmcnt(0)
	v_pk_mul_f32 v[36:37], v[2:3], v[42:43]
	ds_bpermute_b32 v2, v144, v0
	ds_bpermute_b32 v3, v145, v0
	v_pk_mul_f32 v[34:35], v[6:7], v[42:43]
	v_pk_mul_f32 v[38:39], v[10:11], v[42:43]
	v_pk_mul_f32 v[40:41], v[14:15], v[42:43]
	v_pk_mul_f32 v[18:19], v[18:19], v[42:43]
	v_pk_mul_f32 v[22:23], v[22:23], v[42:43]
	v_pk_mul_f32 v[10:11], v[26:27], v[42:43]
	v_pk_mul_f32 v[14:15], v[30:31], v[42:43]
	s_waitcnt lgkmcnt(0)
	v_pk_mul_f32 v[26:27], v[4:5], v[2:3]
	v_pk_mul_f32 v[30:31], v[8:9], v[2:3]
	v_pk_mul_f32 v[42:43], v[12:13], v[2:3]
	v_pk_mul_f32 v[16:17], v[16:17], v[2:3]
	v_pk_mul_f32 v[8:9], v[20:21], v[2:3]
	v_pk_mul_f32 v[12:13], v[24:25], v[2:3]
	v_pk_mul_f32 v[4:5], v[28:29], v[2:3]
	v_pk_mul_f32 v[6:7], v[32:33], v[2:3]
	s_cbranch_vccnz .LBB0_1308
	v_cvt_pk_bf16_f32 v0, v60, v61
	v_cvt_pk_bf16_f32 v2, v68, v69
	ds_write2st64_b32 v129, v0, v2 offset0:108 offset1:109
	v_cvt_pk_bf16_f32 v0, v62, v63
	v_cvt_pk_bf16_f32 v2, v70, v71
	ds_write2st64_b32 v129, v0, v2 offset0:110 offset1:111
	v_cvt_pk_bf16_f32 v0, v64, v65
	v_cvt_pk_bf16_f32 v2, v72, v73
	ds_write2st64_b32 v129, v0, v2 offset0:112 offset1:113
	v_cvt_pk_bf16_f32 v0, v66, v67
	v_cvt_pk_bf16_f32 v2, v74, v75
	ds_write2st64_b32 v129, v0, v2 offset0:114 offset1:115
	v_cvt_pk_bf16_f32 v0, v56, v57
	v_cvt_pk_bf16_f32 v2, v52, v53
	ds_write2st64_b32 v129, v0, v2 offset0:116 offset1:117
	v_cvt_pk_bf16_f32 v0, v58, v59
	v_cvt_pk_bf16_f32 v2, v54, v55
	ds_write2st64_b32 v129, v0, v2 offset0:118 offset1:119
	v_cvt_pk_bf16_f32 v0, v46, v47
	v_cvt_pk_bf16_f32 v2, v44, v45
	ds_write2st64_b32 v129, v0, v2 offset0:120 offset1:121
	v_cvt_pk_bf16_f32 v0, v50, v51
	v_cvt_pk_bf16_f32 v2, v48, v49
	ds_write2st64_b32 v129, v0, v2 offset0:122 offset1:123
	v_cvt_pk_bf16_f32 v0, v36, v37
	v_cvt_pk_bf16_f32 v2, v26, v27
	ds_write2st64_b32 v129, v0, v2 offset0:124 offset1:125
	v_cvt_pk_bf16_f32 v0, v34, v35
	v_cvt_pk_bf16_f32 v2, v30, v31
	ds_write2st64_b32 v129, v0, v2 offset0:126 offset1:127
	v_cvt_pk_bf16_f32 v0, v38, v39
	v_cvt_pk_bf16_f32 v2, v42, v43
	ds_write2st64_b32 v129, v0, v2 offset0:128 offset1:129
	v_cvt_pk_bf16_f32 v0, v40, v41
	v_cvt_pk_bf16_f32 v2, v16, v17
	ds_write2st64_b32 v129, v0, v2 offset0:130 offset1:131
	v_cvt_pk_bf16_f32 v0, v18, v19
	v_cvt_pk_bf16_f32 v2, v8, v9
	ds_write2st64_b32 v129, v0, v2 offset0:132 offset1:133
	v_cvt_pk_bf16_f32 v0, v22, v23
	v_cvt_pk_bf16_f32 v2, v12, v13
	ds_write2st64_b32 v129, v0, v2 offset0:134 offset1:135
	v_cvt_pk_bf16_f32 v0, v10, v11
	v_cvt_pk_bf16_f32 v2, v4, v5
	ds_write2st64_b32 v129, v0, v2 offset0:136 offset1:137
	v_cvt_pk_bf16_f32 v0, v14, v15
	v_cvt_pk_bf16_f32 v2, v6, v7
	s_mov_b64 s[42:43], 0
	ds_write2st64_b32 v129, v0, v2 offset0:138 offset1:139
	s_branch .LBB0_1308
